# mixa: WGs with blockIdx>=256 run GLA-prep items first and latent-attention item last (overlap attention with prep on each CU)
# speedup vs baseline: 1.0269x; 1.0006x over previous
.LBB0_310:
	s_cmp_gt_i32 s44, 3
	s_cselect_b64 s[2:3], -1, 0
	s_cmp_lt_i32 s45, 4
	s_cselect_b64 s[4:5], -1, 0
	v_writelane_b32 v255, s70, 18
	s_or_b64 s[2:3], s[2:3], s[4:5]
	s_and_b64 vcc, exec, s[2:3]
	v_writelane_b32 v255, s71, 19
	v_writelane_b32 v255, s96, 20
	s_cbranch_vccnz .LBB0_404
	s_cmpk_gt_i32 s66, 0x7ff
	s_cbranch_scc1 .LBB0_350
	v_and_b32_e32 v3, 0x3ff, v0
	v_lshlrev_b32_e32 v2, 2, v3
	v_bfe_u32 v120, v0, 2, 8
	v_and_b32_e32 v2, 12, v2
	v_bfe_u32 v134, v0, 6, 4
	v_lshl_add_u32 v4, v120, 6, 32
	v_lshlrev_b32_e32 v5, 2, v2
	s_mov_b32 s2, 0xd000
	v_lshlrev_b32_e32 v137, 4, v134
	v_add3_u32 v121, v4, v5, s2
	v_lshlrev_b32_e32 v4, 3, v3
	v_lshlrev_b32_e32 v5, 4, v3
	v_or_b32_e32 v7, 0x100, v3
	v_or_b32_e32 v9, 0x200, v3
	v_or_b32_e32 v11, 0x300, v3
	v_cmp_gt_u32_e64 s[4:5], 64, v3
	s_waitcnt lgkmcnt(0)
	v_cmp_lt_u32_e64 s[6:7], 63, v3
	v_or_b32_e32 v3, 1, v137
	v_and_b32_e32 v140, 15, v0
	v_and_b32_e32 v66, 0xf0, v5
	v_bfe_u32 v122, v0, 4, 6
	v_mul_u32_u24_e32 v139, 0x88, v3
	v_or_b32_e32 v3, v137, v140
	v_and_b32_e32 v19, 12, v120
	v_add_u32_e32 v5, 32, v66
	v_mul_u32_u24_e32 v6, 0x88, v122
	v_lshrrev_b32_e32 v125, 4, v7
	v_cmp_le_u32_e64 s[2:3], v19, v3
	v_lshl_add_u32 v123, v6, 1, v5
	v_mul_u32_u24_e32 v6, 0x88, v125
	v_lshrrev_b32_e32 v128, 4, v9
	v_writelane_b32 v255, s2, 21
	v_lshl_add_u32 v126, v6, 1, v5
	v_mul_u32_u24_e32 v6, 0x88, v128
	v_lshrrev_b32_e32 v131, 4, v11
	v_writelane_b32 v255, s3, 22
	v_cmp_ge_u32_e64 s[2:3], v19, v3
	v_lshl_add_u32 v129, v6, 1, v5
	v_mul_u32_u24_e32 v6, 0x88, v131
	v_writelane_b32 v255, s2, 23
	v_lshl_add_u32 v132, v6, 1, v5
	v_lshl_add_u32 v135, v134, 10, 32
	v_lshlrev_b32_e32 v6, 9, v134
	v_writelane_b32 v255, s3, 24
	v_cmp_lt_u32_e64 s[2:3], v19, v3
	v_sub_u32_e32 v136, v135, v6
	v_or_b32_e32 v6, 1, v19
	v_writelane_b32 v255, s2, 25
	v_and_b32_e32 v4, 56, v4
	v_bfe_u32 v25, v0, 3, 7
	v_writelane_b32 v255, s3, 26
	v_cmp_ge_u32_e64 s[2:3], v6, v3
	v_or_b32_e32 v6, 2, v19
	s_movk_i32 s9, 0x90
	v_writelane_b32 v255, s2, 27
	v_lshrrev_b32_e32 v7, 3, v7
	s_movk_i32 s8, 0x110
	v_writelane_b32 v255, s3, 28
	v_cmp_le_u32_e64 s[2:3], v6, v3
	v_mul_u32_u24_e32 v14, 0x90, v7
	s_add_u32 s10, s42, 0x12b24000
	v_writelane_b32 v255, s2, 29
	v_mad_u32_u24 v141, v122, s8, v5
	v_mad_u32_u24 v144, v125, s8, v5
	v_writelane_b32 v255, s3, 30
	v_cmp_ge_u32_e64 s[2:3], v6, v3
	v_or_b32_e32 v6, 3, v19
	v_mad_u32_u24 v146, v128, s8, v5
	v_writelane_b32 v255, s2, 31
	v_mad_u32_u24 v148, v131, s8, v5
	v_lshrrev_b32_e32 v5, 3, v11
	v_writelane_b32 v255, s3, 32
	v_cmp_le_u32_e64 s[2:3], v6, v3
	s_addc_u32 s11, s43, 0
	v_mov_b32_e32 v67, 0
	v_writelane_b32 v255, s2, 33
	s_add_u32 s12, s42, 0x1c924000
	v_mad_u32_u24 v13, v3, s8, 32
	v_writelane_b32 v255, s3, 34
	v_cmp_ge_u32_e64 s[2:3], v6, v3
	v_or_b32_e32 v6, 16, v19
	s_waitcnt vmcnt(5)
	v_lshl_add_u64 v[30:31], s[42:43], 0, v[66:67]
	v_writelane_b32 v255, s2, 35
	s_addc_u32 s13, s43, 0
	v_lshlrev_b32_e32 v66, 7, v3
	v_writelane_b32 v255, s3, 36
	v_cmp_le_u32_e64 s[2:3], v6, v3
	v_lshlrev_b32_e32 v22, 6, v5
	v_lshl_add_u64 v[32:33], s[42:43], 0, v[66:67]
	v_writelane_b32 v255, s2, 37
	v_lshlrev_b32_e32 v66, 1, v19
	s_add_u32 s33, s42, 0xd324000
	v_writelane_b32 v255, s3, 38
	v_cmp_ge_u32_e64 s[2:3], v6, v3
	v_or_b32_e32 v6, 17, v19
	v_lshl_add_u64 v[32:33], v[32:33], 0, v[66:67]
	v_writelane_b32 v255, s2, 39
	s_addc_u32 s30, s43, 0
	s_add_u32 s31, s42, 0xdd24000
	v_writelane_b32 v255, s3, 40
	v_cmp_le_u32_e64 s[2:3], v6, v3
	v_and_b32_e32 v15, 48, v0
	v_mov_b32_e32 v69, v67
	v_writelane_b32 v255, s2, 41
	s_addc_u32 s34, s43, 0
	v_add_u32_e32 v17, 32, v15
	v_writelane_b32 v255, s3, 42
	v_cmp_ge_u32_e64 s[2:3], v6, v3
	v_or_b32_e32 v6, 18, v19
	v_mul_u32_u24_e32 v21, 0x110, v140
	v_writelane_b32 v255, s2, 43
	v_lshlrev_b32_e32 v8, 7, v122
	v_lshlrev_b32_e32 v10, 6, v25
	v_writelane_b32 v255, s3, 44
	v_cmp_le_u32_e64 s[2:3], v6, v3
	v_lshlrev_b32_e32 v12, 7, v125
	v_lshlrev_b32_e32 v16, 7, v128
	v_writelane_b32 v255, s2, 45
	v_lshlrev_b32_e32 v20, 7, v131
	v_lshlrev_b32_e32 v24, 10, v140
	v_writelane_b32 v255, s3, 46
	v_cmp_ge_u32_e64 s[2:3], v6, v3
	v_or_b32_e32 v6, 19, v19
	v_lshlrev_b32_e32 v70, 9, v25
	v_writelane_b32 v255, s2, 47
	v_mul_u32_u24_e32 v26, 0x600, v25
	v_lshlrev_b32_e32 v28, 8, v25
	v_writelane_b32 v255, s3, 48
	v_cmp_le_u32_e64 s[2:3], v6, v3
	s_add_u32 s14, s42, 0xb724000
	v_lshlrev_b32_e32 v86, 2, v2
	v_writelane_b32 v255, s2, 49
	v_mbcnt_lo_u32_b32 v2, -1, 0
	v_and_b32_e32 v1, 63, v0
	v_writelane_b32 v255, s3, 50
	v_cmp_ge_u32_e64 s[2:3], v6, v3
	v_or_b32_e32 v6, 32, v19
	v_add_u32_e32 v124, 0x4400, v123
	v_writelane_b32 v255, s2, 51
	v_add_u32_e32 v127, 0x4400, v126
	v_add_u32_e32 v130, 0x4400, v129
	v_writelane_b32 v255, s3, 52
	v_cmp_le_u32_e64 s[2:3], v6, v3
	v_add_u32_e32 v133, 0x4400, v132
	v_mul_u32_u24_e32 v138, 0x880, v134
	v_writelane_b32 v255, s2, 53
	v_mov_b32_e32 v71, v67
	s_movk_i32 s19, 0x4000
	v_writelane_b32 v255, s3, 54
	v_cmp_ge_u32_e64 s[2:3], v6, v3
	v_or_b32_e32 v6, 33, v19
	v_cmp_ge_u32_e64 s[48:49], v6, v3
	v_writelane_b32 v255, s2, 55
	v_or_b32_e32 v72, 0x4000, v70
	v_mov_b32_e32 v73, v67
	v_writelane_b32 v255, s3, 56
	v_cmp_le_u32_e64 s[2:3], v6, v3
	v_or_b32_e32 v6, 34, v19
	v_cmp_le_u32_e64 s[50:51], v6, v3
	v_cmp_ge_u32_e64 s[52:53], v6, v3
	v_or_b32_e32 v6, 35, v19
	v_cmp_le_u32_e64 s[54:55], v6, v3
	v_cmp_ge_u32_e64 s[56:57], v6, v3
	v_or_b32_e32 v6, 48, v19
	v_cmp_le_u32_e64 s[58:59], v6, v3
	v_cmp_ge_u32_e64 s[60:61], v6, v3
	v_or_b32_e32 v6, 49, v19
	v_cmp_le_u32_e64 s[62:63], v6, v3
	v_cmp_ge_u32_e64 s[64:65], v6, v3
	v_or_b32_e32 v6, 50, v19
	v_cmp_le_u32_e64 s[66:67], v6, v3
	v_cmp_ge_u32_e64 s[68:69], v6, v3
	v_or_b32_e32 v6, 51, v19
	v_cmp_le_u32_e64 s[70:71], v6, v3
	v_cmp_ge_u32_e64 s[72:73], v6, v3
	v_lshlrev_b32_e32 v6, 1, v4
	v_add_u32_e32 v23, 32, v6
	v_mad_u32_u24 v142, v25, s9, v23
	s_mov_b32 s9, 0x8800
	v_add3_u32 v145, v23, v14, s9
	v_lshlrev_b32_e32 v14, 6, v7
	v_lshrrev_b32_e32 v7, 3, v9
	v_mul_u32_u24_e32 v9, 0x90, v7
	v_lshlrev_b32_e32 v18, 6, v7
	v_mul_u32_u24_e32 v7, 0x90, v5
	v_add3_u32 v147, v23, v9, s9
	v_add3_u32 v149, v23, v7, s9
	s_mov_b64 s[8:9], 0xe324000
	v_bfe_u32 v5, v0, 1, 9
	v_lshl_add_u64 v[74:75], v[30:31], 0, s[8:9]
	s_mov_b64 s[8:9], 0xef24000
	v_and_b32_e32 v7, 0x60, v5
	v_lshl_add_u64 v[76:77], v[30:31], 0, s[8:9]
	s_mov_b64 s[8:9], 0x1bd24000
	v_or_b32_e32 v150, 0x2000, v7
	v_lshl_add_u64 v[78:79], v[32:33], 0, s[8:9]
	s_mov_b64 s[8:9], 0x9f24000
	v_mov_b32_e32 v7, v67
	v_and_b32_e32 v68, 24, v5
	v_lshl_add_u64 v[80:81], v[30:31], 0, s[8:9]
	v_lshl_add_u64 v[6:7], s[42:43], 0, v[6:7]
	s_mov_b64 s[8:9], 0x1a524000
	v_mul_u32_u24_e32 v5, 0x48, v25
	v_lshl_add_u64 v[82:83], v[6:7], 0, s[8:9]
	v_lshl_add_u64 v[6:7], s[42:43], 0, v[68:69]
	s_mov_b64 s[8:9], 0x15d24000
	v_add_u32_e32 v143, 0x8800, v142
	v_mul_u32_u24_e32 v151, 0x90, v140
	s_addc_u32 s15, s43, 0
	v_lshl_add_u64 v[84:85], v[6:7], 0, s[8:9]
	v_lshl_add_u32 v69, v5, 1, v23
	v_or_b32_e32 v152, 0x80, v25
	s_mov_b32 s17, 0
	s_mov_b32 s35, 0xbfb8aa3b
	s_mov_b32 s78, 0x800000
	s_mov_b32 s79, 0x3f317217
	s_mov_b32 s80, 0x7f800000
	s_mov_b32 s18, 0x3d800000
	s_mov_b32 s81, 0x3fb8aa3b
	v_add_u32_e32 v153, v13, v15
	v_add_u32_e32 v154, v17, v21
	v_lshlrev_b32_e32 v88, 1, v8
	v_lshlrev_b32_e32 v90, 1, v10
	v_lshlrev_b32_e32 v92, 1, v12
	v_lshlrev_b32_e32 v94, 1, v14
	v_lshlrev_b32_e32 v96, 1, v16
	v_lshlrev_b32_e32 v98, 1, v18
	v_lshlrev_b32_e32 v100, 1, v20
	v_lshlrev_b32_e32 v102, 1, v22
	v_lshlrev_b32_e32 v104, 1, v24
	v_lshlrev_b32_e32 v106, 1, v4
	v_lshlrev_b32_e32 v108, 1, v26
	s_mov_b32 s96, 0x18000
	v_lshlrev_b32_e32 v110, 1, v28
	s_mov_b32 s97, 0xf149f2ca
	v_mov_b32_e32 v155, 0x41b17218
	v_mbcnt_hi_u32_b32 v156, -1, v2
	v_readlane_b32 s8, v255, 16
	v_readlane_b32 s9, v255, 17
	s_mov_b32 s98, 0
	s_load_dword s99, s[0:1], 0xf0
	s_waitcnt lgkmcnt(0)
	s_cmp_eq_u32 s99, 0x200
	s_cbranch_scc0 .Lstg_m0_skip
	s_cmp_lt_u32 s8, 0x100
	s_cbranch_scc1 .Lstg_m0_skip
	s_add_u32 s8, s8, 0x200
	s_mov_b32 s98, 1
.Lstg_m0_skip:
	s_nop 0
	v_writelane_b32 v255, s98, 62
	s_branch .LBB0_314
.LBB0_313:
	s_barrier
	s_load_dword s9, s[0:1], 0xf0
	v_readlane_b32 s98, v255, 62
	s_waitcnt lgkmcnt(0)
	s_cmp_eq_u32 s98, 2
	s_cbranch_scc1 .LBB0_350
	s_add_i32 s8, s8, s9
	s_cmpk_lt_i32 s8, 0x800
	s_cbranch_scc1 .LBB0_314
	s_cmp_eq_u32 s98, 1
	s_cbranch_scc0 .LBB0_350
	s_mov_b32 s98, 2
	s_nop 0
	v_writelane_b32 v255, s98, 62
	s_sub_i32 s8, s8, 0x800

.LBB0_1050:
	s_cmp_gt_i32 s44, 12
	s_cselect_b64 s[2:3], -1, 0
	s_cmp_lt_i32 s45, 13
	s_cselect_b64 s[4:5], -1, 0
	s_or_b64 s[2:3], s[2:3], s[4:5]
	s_and_b64 vcc, exec, s[2:3]
	s_cbranch_vccnz .LBB0_1144
	s_cmpk_gt_i32 s66, 0x7ff
	s_cbranch_scc1 .LBB0_1090
	v_and_b32_e32 v3, 0x3ff, v0
	v_lshlrev_b32_e32 v2, 2, v3
	v_bfe_u32 v120, v0, 2, 8
	v_and_b32_e32 v2, 12, v2
	v_lshl_add_u32 v4, v120, 6, 32
	v_lshlrev_b32_e32 v5, 2, v2
	s_mov_b32 s2, 0xd000
	v_lshlrev_b32_e32 v138, 4, v131
	v_add3_u32 v121, v4, v5, s2
	v_lshlrev_b32_e32 v4, 3, v3
	v_lshlrev_b32_e32 v5, 4, v3
	s_waitcnt vmcnt(6)
	v_or_b32_e32 v7, 0x100, v3
	v_or_b32_e32 v9, 0x200, v3
	s_waitcnt vmcnt(4)
	v_or_b32_e32 v11, 0x300, v3
	v_cmp_gt_u32_e64 s[4:5], 64, v3
	s_waitcnt lgkmcnt(0)
	v_cmp_lt_u32_e64 s[6:7], 63, v3
	v_or_b32_e32 v3, 1, v138
	v_and_b32_e32 v141, 15, v0
	v_and_b32_e32 v66, 0xf0, v5
	v_bfe_u32 v122, v0, 4, 6
	v_mul_u32_u24_e32 v140, 0x88, v3
	v_or_b32_e32 v3, v138, v141
	v_and_b32_e32 v19, 12, v120
	v_add_u32_e32 v5, 32, v66
	v_mul_u32_u24_e32 v6, 0x88, v122
	v_lshrrev_b32_e32 v125, 4, v7
	v_cmp_le_u32_e64 s[2:3], v19, v3
	v_lshl_add_u32 v123, v6, 1, v5
	v_mul_u32_u24_e32 v6, 0x88, v125
	v_lshrrev_b32_e32 v128, 4, v9
	v_writelane_b32 v255, s2, 21
	v_lshl_add_u32 v126, v6, 1, v5
	v_mul_u32_u24_e32 v6, 0x88, v128
	v_lshrrev_b32_e32 v133, 4, v11
	v_writelane_b32 v255, s3, 22
	v_cmp_ge_u32_e64 s[2:3], v19, v3
	v_lshl_add_u32 v129, v6, 1, v5
	v_mul_u32_u24_e32 v6, 0x88, v133
	v_writelane_b32 v255, s2, 23
	v_lshl_add_u32 v134, v6, 1, v5
	v_lshl_add_u32 v136, v131, 10, 32
	v_lshlrev_b32_e32 v6, 9, v131
	v_writelane_b32 v255, s3, 24
	v_cmp_lt_u32_e64 s[2:3], v19, v3
	v_sub_u32_e32 v137, v136, v6
	v_or_b32_e32 v6, 1, v19
	v_writelane_b32 v255, s2, 25
	v_and_b32_e32 v4, 56, v4
	s_waitcnt vmcnt(3)
	v_bfe_u32 v25, v0, 3, 7
	v_writelane_b32 v255, s3, 26
	v_cmp_ge_u32_e64 s[2:3], v6, v3
	v_or_b32_e32 v6, 2, v19
	s_movk_i32 s9, 0x90
	v_writelane_b32 v255, s2, 27
	v_lshrrev_b32_e32 v7, 3, v7
	s_add_u32 s84, s42, 0x12b24000
	v_writelane_b32 v255, s3, 28
	v_cmp_le_u32_e64 s[2:3], v6, v3
	v_mov_b32_e32 v67, 0
	s_movk_i32 s8, 0x110
	v_writelane_b32 v255, s2, 29
	s_waitcnt vmcnt(2)
	v_mul_u32_u24_e32 v14, 0x90, v7
	s_addc_u32 s85, s43, 0
	v_writelane_b32 v255, s3, 30
	v_cmp_ge_u32_e64 s[2:3], v6, v3
	v_or_b32_e32 v6, 3, v19
	v_mad_u32_u24 v142, v122, s8, v5
	v_writelane_b32 v255, s2, 31
	v_mad_u32_u24 v145, v125, s8, v5
	v_mad_u32_u24 v147, v128, s8, v5
	v_writelane_b32 v255, s3, 32
	v_cmp_le_u32_e64 s[2:3], v6, v3
	v_mad_u32_u24 v149, v133, s8, v5
	v_lshrrev_b32_e32 v5, 3, v11
	v_writelane_b32 v255, s2, 33
	s_waitcnt vmcnt(0)
	v_lshl_add_u64 v[30:31], s[42:43], 0, v[66:67]
	s_mov_b64 s[10:11], 0xe324000
	v_writelane_b32 v255, s3, 34
	v_cmp_ge_u32_e64 s[2:3], v6, v3
	v_or_b32_e32 v6, 16, v19
	s_add_u32 s86, s42, 0x1c924000
	v_writelane_b32 v255, s2, 35
	v_lshlrev_b32_e32 v66, 7, v3
	v_lshlrev_b32_e32 v22, 6, v5
	v_writelane_b32 v255, s3, 36
	v_cmp_le_u32_e64 s[2:3], v6, v3
	v_lshl_add_u64 v[74:75], v[30:31], 0, s[10:11]
	s_mov_b64 s[10:11], 0xef24000
	v_writelane_b32 v255, s2, 37
	s_addc_u32 s87, s43, 0
	v_lshl_add_u64 v[32:33], s[42:43], 0, v[66:67]
	v_writelane_b32 v255, s3, 38
	v_cmp_ge_u32_e64 s[2:3], v6, v3
	v_or_b32_e32 v6, 17, v19
	v_lshlrev_b32_e32 v66, 1, v19
	v_writelane_b32 v255, s2, 39
	v_lshl_add_u64 v[76:77], v[30:31], 0, s[10:11]
	v_lshl_add_u64 v[32:33], v[32:33], 0, v[66:67]
	v_writelane_b32 v255, s3, 40
	v_cmp_le_u32_e64 s[2:3], v6, v3
	s_mov_b64 s[10:11], 0x1bd24000
	s_add_u32 s33, s42, 0xd324000
	v_writelane_b32 v255, s2, 41
	v_lshl_add_u64 v[78:79], v[32:33], 0, s[10:11]
	s_mov_b64 s[10:11], 0x9f24000
	v_writelane_b32 v255, s3, 42
	v_cmp_ge_u32_e64 s[2:3], v6, v3
	v_or_b32_e32 v6, 18, v19
	v_cmp_ge_u32_e64 s[36:37], v6, v3
	v_writelane_b32 v255, s2, 43
	s_addc_u32 s20, s43, 0
	v_mov_b32_e32 v69, v67
	v_writelane_b32 v255, s3, 44
	v_cmp_le_u32_e64 s[2:3], v6, v3
	v_or_b32_e32 v6, 19, v19
	v_cmp_le_u32_e64 s[78:79], v6, v3
	v_writelane_b32 v255, s2, 45
	v_cmp_ge_u32_e64 s[80:81], v6, v3
	v_or_b32_e32 v6, 32, v19
	v_writelane_b32 v255, s3, 46
	v_cmp_le_u32_e64 s[82:83], v6, v3
	v_cmp_ge_u32_e64 s[2:3], v6, v3
	v_or_b32_e32 v6, 33, v19
	v_cmp_le_u32_e64 s[46:47], v6, v3
	v_cmp_ge_u32_e64 s[48:49], v6, v3
	v_or_b32_e32 v6, 34, v19
	v_cmp_le_u32_e64 s[50:51], v6, v3
	v_cmp_ge_u32_e64 s[52:53], v6, v3
	v_or_b32_e32 v6, 35, v19
	v_cmp_le_u32_e64 s[54:55], v6, v3
	v_cmp_ge_u32_e64 s[56:57], v6, v3
	v_or_b32_e32 v6, 48, v19
	v_cmp_le_u32_e64 s[58:59], v6, v3
	v_cmp_ge_u32_e64 s[60:61], v6, v3
	v_or_b32_e32 v6, 49, v19
	v_cmp_le_u32_e64 s[62:63], v6, v3
	v_cmp_ge_u32_e64 s[64:65], v6, v3
	v_or_b32_e32 v6, 50, v19
	v_cmp_le_u32_e64 s[66:67], v6, v3
	v_cmp_ge_u32_e64 s[68:69], v6, v3
	v_or_b32_e32 v6, 51, v19
	v_cmp_le_u32_e64 s[70:71], v6, v3
	v_cmp_ge_u32_e64 s[72:73], v6, v3
	v_lshlrev_b32_e32 v6, 1, v4
	v_add_u32_e32 v23, 32, v6
	v_mad_u32_u24 v143, v25, s9, v23
	s_mov_b32 s9, 0x8800
	v_add3_u32 v146, v23, v14, s9
	v_lshlrev_b32_e32 v14, 6, v7
	v_lshrrev_b32_e32 v7, 3, v9
	v_mul_u32_u24_e32 v9, 0x90, v7
	v_lshlrev_b32_e32 v18, 6, v7
	v_mul_u32_u24_e32 v7, 0x90, v5
	v_bfe_u32 v5, v0, 1, 9
	v_add3_u32 v150, v23, v7, s9
	v_and_b32_e32 v7, 0x60, v5
	v_or_b32_e32 v151, 0x2000, v7
	v_mov_b32_e32 v7, v67
	v_and_b32_e32 v68, 24, v5
	v_lshl_add_u64 v[80:81], v[30:31], 0, s[10:11]
	v_lshl_add_u64 v[6:7], s[42:43], 0, v[6:7]
	s_mov_b64 s[10:11], 0x1a524000
	s_add_u32 s21, s42, 0xdd24000
	v_and_b32_e32 v15, 48, v0
	v_lshl_add_u64 v[82:83], v[6:7], 0, s[10:11]
	s_addc_u32 s22, s43, 0
	v_lshl_add_u64 v[6:7], s[42:43], 0, v[68:69]
	s_mov_b64 s[10:11], 0x15d24000
	v_mad_u32_u24 v13, v3, s8, 32
	v_add_u32_e32 v17, 32, v15
	v_mul_u32_u24_e32 v21, 0x110, v141
	v_lshlrev_b32_e32 v8, 7, v122
	v_lshlrev_b32_e32 v10, 6, v25
	v_lshlrev_b32_e32 v12, 7, v125
	v_lshlrev_b32_e32 v16, 7, v128
	v_lshlrev_b32_e32 v20, 7, v133
	v_lshlrev_b32_e32 v24, 10, v141
	v_lshlrev_b32_e32 v70, 9, v25
	v_mul_u32_u24_e32 v26, 0x600, v25
	v_mul_u32_u24_e32 v5, 0x48, v25
	v_lshlrev_b32_e32 v28, 8, v25
	s_add_u32 s94, s42, 0xb724000
	v_lshl_add_u64 v[84:85], v[6:7], 0, s[10:11]
	v_lshlrev_b32_e32 v86, 2, v2
	v_mbcnt_lo_u32_b32 v2, -1, 0
	v_readlane_b32 s10, v255, 16
	v_and_b32_e32 v1, 63, v0
	v_add_u32_e32 v124, 0x4400, v123
	v_add_u32_e32 v127, 0x4400, v126
	v_add_u32_e32 v132, 0x4400, v129
	v_add_u32_e32 v135, 0x4400, v134
	v_mul_u32_u24_e32 v139, 0x880, v131
	v_add_u32_e32 v144, 0x8800, v143
	v_add3_u32 v148, v23, v9, s9
	v_mov_b32_e32 v71, v67
	s_movk_i32 s9, 0x4000
	v_or_b32_e32 v72, 0x4000, v70
	v_mov_b32_e32 v73, v67
	v_mul_u32_u24_e32 v152, 0x90, v141
	s_addc_u32 s95, s43, 0
	v_lshl_add_u32 v69, v5, 1, v23
	v_or_b32_e32 v153, 0x80, v25
	s_mov_b32 s97, 0
	s_mov_b32 s23, 0xbfb8aa3b
	s_mov_b32 s24, 0x800000
	s_mov_b32 s25, 0x3f317217
	s_mov_b32 s26, 0x7f800000
	s_mov_b32 s8, 0x3d800000
	s_mov_b32 s27, 0x3fb8aa3b
	v_add_u32_e32 v154, v13, v15
	v_add_u32_e32 v155, v17, v21
	v_lshlrev_b32_e32 v88, 1, v8
	v_lshlrev_b32_e32 v90, 1, v10
	v_lshlrev_b32_e32 v92, 1, v12
	v_lshlrev_b32_e32 v94, 1, v14
	v_lshlrev_b32_e32 v96, 1, v16
	v_lshlrev_b32_e32 v98, 1, v18
	v_lshlrev_b32_e32 v100, 1, v20
	v_lshlrev_b32_e32 v102, 1, v22
	v_lshlrev_b32_e32 v104, 1, v24
	v_lshlrev_b32_e32 v106, 1, v4
	v_lshlrev_b32_e32 v108, 1, v26
	s_mov_b32 s28, 0x18000
	v_lshlrev_b32_e32 v110, 1, v28
	s_mov_b32 s29, 0xf149f2ca
	v_mov_b32_e32 v156, 0x41b17218
	v_mbcnt_hi_u32_b32 v157, -1, v2
	s_mov_b32 s30, s10
	v_readlane_b32 s11, v255, 17
	s_mov_b32 s98, 0
	s_load_dword s99, s[0:1], 0xf0
	s_waitcnt lgkmcnt(0)
	s_cmp_eq_u32 s99, 0x200
	s_cbranch_scc0 .Lstg_m1_skip
	s_cmp_lt_u32 s30, 0x100
	s_cbranch_scc1 .Lstg_m1_skip
	s_add_u32 s30, s30, 0x200
	s_mov_b32 s98, 1

.LBB0_1053:
	s_barrier
	s_load_dword s10, s[0:1], 0xf0
	v_readlane_b32 s98, v255, 62
	s_waitcnt lgkmcnt(0)
	s_cmp_eq_u32 s98, 2
	s_cbranch_scc1 .LBB0_1090
	s_add_i32 s30, s30, s10
	s_cmpk_lt_i32 s30, 0x800
	s_cbranch_scc1 .LBB0_1054
	s_cmp_eq_u32 s98, 1
	s_cbranch_scc0 .LBB0_1090
	s_mov_b32 s98, 2
	s_nop 0
	v_writelane_b32 v255, s98, 62
	s_sub_i32 s30, s30, 0x800
